# v030 plus non-temporal PP z-gate loads and no sleep between rendezvous polls
# baseline (speedup 1.0000x reference)
; DI unsigned xb_ld(unsigned* p)              { return __hip_atomic_load(p, __ATOMIC_RELAXED, __HIP_MEMORY_SCOPE_AGENT); }
; DI unsigned xb_add(unsigned* p, unsigned v) { return __hip_atomic_fetch_add(p, v, __ATOMIC_RELAXED, __HIP_MEMORY_SCOPE_AGENT); }
; #define XB_SPIN(cond, bar) do { unsigned _sp = 0; while (cond) { __builtin_amdgcn_s_sleep(1); \
;     if ((++_sp & 255u) == 0u) { if (xb_ld(&(bar)[XB_TMO])) break; if (_sp > XB_SPIN_CAP) { atomicAdd(&(bar)[XB_TMO], 1u); break; } } } } while (0)
; DI void xcd_barrier(const XcdBarrier& b) {
;     asm volatile("s_waitcnt vmcnt(0)" ::: "memory");
;     __syncthreads();
;     if (threadIdx.x == 0) {
;         unsigned* bar = b.bar;
;         __builtin_amdgcn_s_waitcnt(0);
;         unsigned nloc = b.st[0], nx = b.st[1];
;         if (nloc == 0u) { xcd_barrier_complete(bar, b.x, nloc, nx); b.st[0] = nloc; b.st[1] = nx; }
;         const unsigned old = xb_add(&bar[XB_XSUB(b.x)], 1u);
;         const unsigned gen = old / nloc;
;         if (old + 1u == (gen + 1u) * nloc) {
;             __builtin_amdgcn_fence(__ATOMIC_RELEASE, "agent");
;             asm volatile("s_waitcnt vmcnt(0)" ::: "memory");
;             const unsigned og = xb_add(&bar[XB_TOP], 1u);
;             const unsigned tg = og / nx;
;             if (og + 1u == (tg + 1u) * nx) xb_add(&bar[XB_TOPGEN], 1u);
;             else XB_SPIN(xb_ld(&bar[XB_TOPGEN]) == tg, bar);
;             __builtin_amdgcn_fence(__ATOMIC_ACQUIRE, "agent");
;             xb_add(&bar[XB_XGEN(b.x)], 1u);
;             asm volatile("s_waitcnt vmcnt(0)" ::: "memory");
;         } else {
;             XB_SPIN(xb_ld(&bar[XB_TOPGEN]) == gen, bar);
;             __builtin_amdgcn_fence(__ATOMIC_ACQUIRE, "agent");
;             asm volatile("s_waitcnt vmcnt(0)" ::: "memory");
;         }
;     }
;     __syncthreads();
.Lppg2_poll:
	global_load_dword v148, v146, s[40:41] sc1
	s_waitcnt vmcnt(0)
	v_readfirstlane_b32 s6, v148
	s_cmp_ge_u32 s6, s42
	s_cbranch_scc1 .Lppg2_done
	s_add_i32 s43, s43, 1
	s_nop 0
	s_cmp_lt_u32 s43, 0x400000
	s_cbranch_scc1 .Lppg2_poll
